# v|z GEMM: last seven of sixteen output stores of each unit held in spare registers and issued one per K-loop pass of the next unit (flushed after the last unit)
# baseline (speedup 1.0000x reference)
; #define PG8_STAGE(bufoff, gbase, voff) do { _Pragma("unroll") for (int _i = 0; _i < 2; ++_i) \
;         __builtin_amdgcn_global_load_lds((const unsigned*)((const char*)(gbase) + (voff)[_i]), (PG8_LAS unsigned*)(lds + (bufoff) + ldsw + _i * 8192), 16, 0, 0); } while (0)
; #define PG8_WAIT_V(n) asm volatile("s_waitcnt vmcnt(" #n ")" ::: "memory")
; #define PG8_BAR __builtin_amdgcn_s_barrier()
; template <class Epi, class Sched, bool ALIGN_EPI = false, bool SP2 = false>
; __device__ __forceinline__ void gemm_phase(PG8_LAS unsigned char* lds, const Gemm g, const Sched& S, const Epi& E, const int tid_in) {
;     const int tid = tid_in, wid = __builtin_amdgcn_readfirstlane(tid >> 6), lane = tid & 63, wr = wid >> 2, wc = wid & 3, fr = lane & 15, fq = lane >> 4;
;     const int K = g.K, nt = K / BK;
;     unsigned voffA[2], voffB[2];
; #pragma unroll
;     for (int i = 0; i < 2; ++i) { int R, C; stage_rc(tid * 16 + i * 8192, R, C); const int Rb = Epi::PERM ? ((R & ~31) + perm32(R & 31)) : R;
;         voffA[i] = (unsigned)(R * K + C) * 2u; voffB[i] = (unsigned)(Rb * K + C) * 2u; }
;     const size_t kstep = (size_t)(BK * 2);
;     const size_t hstep = (size_t)HALF * K * 2;
;     const size_t tstep = 2 * hstep;
;     const unsigned ldsw = (unsigned)wid * 1024u;
;     const int aoff = lds_byte(wr * 64 + fr, fq * 8), boff = lds_byte(wc * 32 + fr, fq * 8);
;     ...
;     Unit cur, nxt; int ui = 0;
;     if (!S.next(0, cur)) return;
;     f32x4 acc[2][2][4][2];
; #pragma unroll
;     for (int a = 0; a < 2; ++a)
; #pragma unroll
;         for (int b = 0; b < 2; ++b)
; #pragma unroll
;             for (int m = 0; m < 4; ++m)
; #pragma unroll
;                 for (int n = 0; n < 2; ++n) acc[a][b][m][n] = (f32x4){0.f, 0.f, 0.f, 0.f};
;     bf16x8 At[4][2], B0[2][2], B1[2][2];
;     const char* cA = (const char*)g.asel(cur.pn) + (size_t)cur.pm * tstep; const char* cB = (const char*)g.Bt + (size_t)cur.pn * tstep;
;     S.a_ready(cur);
;     if constexpr (SP2) {
;         PG8_STAGE(PG8_SB(0, 0), cB, voffB); PG8_STAGE(PG8_SB(0, 1), cB + hstep, voffB); PG8_STAGE(PG8_SA(0, 0), cA, voffA); PG8_STAGE(PG8_SA(0, 1), cA + hstep, voffA);
;         if (wr == 1) PG8_BAR;
;         PG8_WAIT_V(2); PG8_BAR;
;         PG8_STAGE(PG8_SB(1, 0), cB + kstep, voffB); PG8_STAGE(PG8_SA(1, 0), cA + kstep, voffA); PG8_STAGE(PG8_SB(1, 1), cB + hstep + kstep, voffB);
;         PG8_WAIT_V(6); PG8_BAR;
.LBB0_725:
	s_mov_b32 s98, 0
	v_readlane_b32 s2, v254, 1
	v_readlane_b32 s3, v254, 2
	s_cmp_lt_i32 s2, 9
	s_cselect_b64 s[2:3], -1, 0
	s_and_b64 s[8:9], s[2:3], s[0:1]
	s_andn2_b64 vcc, exec, s[8:9]
	s_cbranch_vccnz .LBB0_746
	v_mbcnt_lo_u32_b32 v8, -1, 0
	v_mbcnt_hi_u32_b32 v8, -1, v8
	s_cmpk_gt_i32 s84, 0x3ff
	v_add_u32_e32 v0, s52, v8
	s_mov_b64 s[0:1], s[82:83]
	v_readfirstlane_b32 s2, v0
	s_cbranch_scc1 .LBB0_746
	v_lshlrev_b32_e32 v1, 4, v0
	v_add_u32_e32 v2, 0x2000, v1
	v_ashrrev_i32_e32 v3, 31, v2
	v_lshrrev_b32_e32 v3, 22, v3
	v_add_u32_e32 v3, v2, v3
	v_ashrrev_i32_e32 v9, 10, v3
	v_mul_i32_i24_e32 v3, 0x400, v9
	v_sub_u32_e32 v2, v2, v3
	v_lshrrev_b32_e32 v3, 4, v2
	v_bitop3_b32 v2, v3, v2, 32 bitop3:0x6c
	v_ashrrev_i32_e32 v3, 31, v2
	v_lshrrev_b32_e32 v3, 26, v3
	v_add_u32_e32 v3, v2, v3
	v_lshlrev_b32_e32 v4, 3, v9
	v_ashrrev_i32_e32 v10, 6, v3
	v_and_b32_e32 v4, -16, v4
	v_add_u32_e32 v4, v10, v4
	s_load_dwordx4 s[4:7], s[0:1], 0xc0
	v_and_b32_e32 v5, 3, v10
	s_mov_b32 s0, 0x1fffe0
	v_lshrrev_b32_e32 v6, 2, v4
	v_lshlrev_b32_e32 v7, 1, v4
	v_and_b32_e32 v3, 0xc0, v3
	v_and_or_b32 v5, v4, s0, v5
	v_and_b32_e32 v6, 4, v6
	v_and_b32_e32 v7, 24, v7
	v_sub_u32_e32 v2, v2, v3
	v_mov_b32_e32 v3, 1
	v_or3_b32 v5, v5, v6, v7
	v_lshlrev_b32_e32 v6, 5, v9
	v_ashrrev_i16_sdwa v2, v3, sext(v2) dst_sel:DWORD dst_unused:UNUSED_PAD src0_sel:DWORD src1_sel:BYTE_0
	v_and_b32_e32 v6, 32, v6
	v_bfe_i32 v11, v2, 0, 16
	v_add_lshl_u32 v2, v6, v11, 1
	v_lshl_add_u32 v128, v5, 11, v2
	v_lshl_add_u32 v130, v4, 11, v2
	v_bfe_i32 v2, v0, 27, 1
	v_lshrrev_b32_e32 v2, 22, v2
	v_add_u32_e32 v2, v1, v2
	v_and_b32_e32 v2, 0xfffffc00, v2
	v_sub_u32_e32 v1, v1, v2
	v_lshrrev_b32_e32 v2, 4, v1
	v_ashrrev_i32_e32 v4, 31, v0
	s_waitcnt lgkmcnt(0)
	s_add_u32 s33, s6, 0x8000000
	v_bitop3_b32 v1, v2, v1, 32 bitop3:0x6c
	v_lshrrev_b32_e32 v4, 26, v4
	s_addc_u32 s36, s7, 0
	v_ashrrev_i32_e32 v2, 31, v1
	v_add_u32_e32 v0, v0, v4
	s_add_u32 s37, s6, 0x1100000
	v_lshrrev_b32_e32 v2, 26, v2
	v_ashrrev_i32_e32 v13, 6, v0
	s_addc_u32 s38, s7, 0
	v_add_u32_e32 v2, v1, v2
	v_lshlrev_b32_e32 v0, 3, v13
	s_add_u32 s39, s6, 0xc000000
	v_ashrrev_i32_e32 v12, 6, v2
	v_and_b32_e32 v0, -16, v0
	s_addc_u32 s40, s7, 0
	v_add_u32_e32 v0, v12, v0
	v_and_b32_e32 v4, 3, v12
	s_ashr_i32 s42, s84, 31
	v_and_or_b32 v4, v0, s0, v4
	s_lshr_b32 s0, s42, 29
	s_add_i32 s0, s84, s0
	s_and_b32 s1, s0, -8
	s_ashr_i32 s14, s2, 6
	s_sub_i32 s1, s84, s1
	s_ashr_i32 s3, s2, 8
	s_lshl_b32 s41, s14, 10
	s_lshl_b32 s11, s1, 7
	s_ashr_i32 s0, s0, 3
	s_mul_i32 s10, s1, 0x81
	s_cmp_lt_i32 s1, 0
	s_cselect_b32 s1, s10, s11
	s_add_i32 s1, s1, s0
	s_mul_hi_i32 s0, s1, 0x2aaaaaab
	s_lshr_b32 s10, s0, 31
	s_ashr_i32 s0, s0, 3
	v_lshrrev_b32_e32 v5, 2, v0
	v_lshlrev_b32_e32 v6, 1, v0
	v_and_b32_e32 v2, 0xc0, v2
	s_add_i32 s0, s0, s10
	v_and_b32_e32 v5, 4, v5
	v_and_b32_e32 v6, 24, v6
	v_sub_u32_e32 v1, v1, v2
	s_mul_i32 s10, s0, 6
	v_or3_b32 v4, v4, v5, v6
	v_lshlrev_b32_e32 v5, 5, v13
	v_ashrrev_i16_sdwa v1, v3, sext(v1) dst_sel:DWORD dst_unused:UNUSED_PAD src0_sel:DWORD src1_sel:BYTE_0
	s_sub_i32 s11, 0x80, s10
	s_mul_i32 s0, s0, 48
	v_and_b32_e32 v5, 32, v5
	v_bfe_i32 v14, v1, 0, 16
	s_min_u32 s11, s11, 6
	s_sub_i32 s12, s1, s0
	v_add_lshl_u32 v1, v5, v14, 1
	s_sext_i32_i8 s0, s12
	v_cvt_f32_ubyte0_e32 v3, s11
	v_lshl_add_u32 v132, v4, 11, v1
	v_cvt_f32_i32_e32 v2, s0
	v_rcp_iflag_f32_e32 v4, v3
	v_lshl_add_u32 v134, v0, 11, v1
	s_ashr_i32 s0, s0, 30
	s_or_b32 s13, s0, 1
	v_mul_f32_e32 v0, v2, v4
	v_trunc_f32_e32 v0, v0
	v_fma_f32 v1, -v0, v3, v2
	v_cvt_i32_f32_e32 v0, v0
	v_cmp_ge_f32_e64 s[0:1], |v1|, v3
	s_and_b64 s[0:1], s[0:1], exec
	s_cselect_b32 s0, s13, 0
	v_readfirstlane_b32 s1, v0
	s_add_i32 s0, s1, s0
	s_mul_i32 s11, s0, s11
	s_sub_i32 s11, s12, s11
	s_sext_i32_i8 s11, s11
	s_bfe_i32 s1, s0, 0x80000
	s_add_i32 s28, s10, s11
	s_sext_i32_i16 s63, s1
	s_ashr_i32 s29, s28, 31
	s_bfe_i64 s[0:1], s[0:1], 0x80000
	s_lshl_b64 s[10:11], s[28:29], 19
	s_lshl_b64 s[0:1], s[0:1], 19
	s_add_u32 s30, s37, s0
	s_addc_u32 s31, s38, s1
	s_add_i32 s29, s41, 0
	s_add_i32 m0, s29, 0x10000
	s_add_i32 s0, s29, 0x12000
	s_cmp_lt_i32 s63, 4
	global_load_lds_dwordx4 v132, s[30:31]
	s_mov_b32 m0, s0
	s_cselect_b32 s12, s36, s40
	s_cselect_b32 s13, s33, s39
	s_add_u32 s0, s30, 0x40000
	global_load_lds_dwordx4 v128, s[30:31]
	s_addc_u32 s1, s31, 0
	s_add_i32 m0, s29, 0x14000
	v_mov_b32_e32 v133, 0
	global_load_lds_dwordx4 v132, s[0:1]
	s_add_i32 m0, s29, 0x16000
	v_mov_b32_e32 v129, v133
	global_load_lds_dwordx4 v128, s[0:1]
	s_add_u32 s0, s13, s10
	s_addc_u32 s1, s12, s11
	s_add_i32 s43, s29, 0x2000
	s_mov_b32 m0, s29
	s_add_u32 s10, s0, 0x40000
	global_load_lds_dwordx4 v134, s[0:1]
	s_mov_b32 m0, s43
	s_addc_u32 s11, s1, 0
	s_add_i32 s44, s29, 0x4000
	global_load_lds_dwordx4 v130, s[0:1]
	s_mov_b32 m0, s44
	s_add_i32 s45, s29, 0x6000
	global_load_lds_dwordx4 v134, s[10:11]
	s_mov_b32 m0, s45
	v_mov_b32_e32 v135, v133
	global_load_lds_dwordx4 v130, s[10:11]
	v_mov_b32_e32 v131, v133
	s_cmp_eq_u32 s3, 1
	s_mov_b32 s46, 0
	v_lshl_add_u64 v[6:7], s[30:31], 0, v[132:133]
	v_lshl_add_u64 v[2:3], s[30:31], 0, v[128:129]
	s_mov_b64 s[10:11], 0x40000
	v_lshl_add_u64 v[0:1], s[0:1], 0, v[134:135]
	s_cselect_b64 s[12:13], -1, 0
	s_cmp_lg_u32 s3, 1
	v_lshl_add_u64 v[4:5], s[0:1], 0, v[130:131]
	s_cbranch_scc1 .LBB0_729
	s_barrier

; __device__ __forceinline__ u32x4 pack8(const f32x4 a, const f32x4 b) { u32x4 w; w.x = cvt_pk_bf16(a[0], a[1]); w.y = cvt_pk_bf16(a[2], a[3]); w.z = cvt_pk_bf16(b[0], b[1]); w.w = cvt_pk_bf16(b[2], b[3]); return w; }
; #define PG8_STAGE(bufoff, gbase, voff) do { _Pragma("unroll") for (int _i = 0; _i < 2; ++_i) \
;         __builtin_amdgcn_global_load_lds((const unsigned*)((const char*)(gbase) + (voff)[_i]), (PG8_LAS unsigned*)(lds + (bufoff) + ldsw + _i * 8192), 16, 0, 0); } while (0)
; #define PG8_LDA(dst, b, h) do { _Pragma("unroll") for (int m = 0; m < 4; ++m) _Pragma("unroll") for (int k = 0; k < 2; ++k) dst[m][k] = *(const PG8_LAS bf16x8*)(lds + PG8_SA(b, h) + aoff + m * 2048 + k * 1024); } while (0)
; #define PG8_LDB(dst, b, h) do { _Pragma("unroll") for (int n = 0; n < 2; ++n) _Pragma("unroll") for (int k = 0; k < 2; ++k) dst[n][k] = *(const PG8_LAS bf16x8*)(lds + PG8_SB(b, h) + boff + n * 2048 + k * 1024); } while (0)
; #define PG8_MMA(ai, bj, At, Bt) do { __builtin_amdgcn_s_setprio(1); _Pragma("unroll") for (int m = 0; m < 4; ++m) _Pragma("unroll") for (int n = 0; n < 2; ++n) _Pragma("unroll") for (int k = 0; k < 2; ++k) \
;         acc[ai][bj][m][n] = __builtin_amdgcn_mfma_f32_16x16x32_bf16(Bt[n][k], At[m][k], acc[ai][bj][m][n], 0, 0, 0); __builtin_amdgcn_s_setprio(0); } while (0)
; #define PG8_BAR __builtin_amdgcn_s_barrier()
;     __device__ __forceinline__ void operator()(const f32x4 (&acc)[2][2][4][2], const Unit& u, int wr, int wc, int fr, int fq) const {
;     ...
;             for (int m = 0; m < 4; ++m) { bf16_t* rowp = O + (size_t)(row0 + ai * HALF + m * 16) * ldc + col0;
; #pragma unroll
;                 for (int bj = 0; bj < 2; ++bj) *(u32x4*)(rowp + bj * HALF) = pack8(acc[ai][bj][m][0], acc[ai][bj][m][1]); }
; template <class Epi, class Sched, bool ALIGN_EPI = false, bool SP2 = false>
; __device__ __forceinline__ void gemm_phase(PG8_LAS unsigned char* lds, const Gemm g, const Sched& S, const Epi& E, const int tid_in) {
;     ...
;             if constexpr (SP2) {
;             PG8_LDB(B0, 0, 0); PG8_LDB(B1, 0, 1); PG8_SCHED; PG8_LDA(At, 0, 0); PG8_STAGE(PG8_SA(1, 1), a1 + hstep, voffA);
;             PG8_WAIT_V(8); PG8_WAIT_L(0); PG8_BAR; PG8_MMA(0, 0, At, B0); PG8_MMA(0, 1, At, B1); PG8_BAR; PG8_SCHED;
;             PG8_LDA(At, 0, 1); PG8_STAGE(PG8_SB(0, 0), b2, voffB); PG8_STAGE(PG8_SB(0, 1), b2 + hstep, voffB); PG8_STAGE(PG8_SA(0, 0), a2, voffA);
.LBB0_739:
	ds_read_b128 v[152:155], v149
	ds_read_b128 v[156:159], v149 offset:1024
	ds_read_b128 v[160:163], v149 offset:2048
	ds_read_b128 v[164:167], v149 offset:3072
	ds_read_b128 v[168:171], v150
	ds_read_b128 v[172:175], v150 offset:1024
	ds_read_b128 v[176:179], v150 offset:2048
	ds_read_b128 v[180:183], v150 offset:3072
	s_add_u32 s30, s0, 0xfffc0080
	s_addc_u32 s31, s1, -1
	s_cmp_eq_u32 s68, 12
	s_cselect_b32 s35, s23, s31
	s_cselect_b32 s34, s64, s30
	s_cselect_b32 s31, s21, s67
	s_cselect_b32 s30, s65, s66
	v_lshl_add_u64 v[144:145], s[0:1], 0, v[136:137]
	s_add_i32 m0, s29, 0xc000
	ds_read_b128 v[184:187], v151
	ds_read_b128 v[188:191], v151 offset:1024
	ds_read_b128 v[192:195], v151 offset:2048
	ds_read_b128 v[196:199], v151 offset:3072
	ds_read_b128 v[200:203], v151 offset:4096
	ds_read_b128 v[204:207], v151 offset:5120
	ds_read_b128 v[208:211], v151 offset:6144
	ds_read_b128 v[212:215], v151 offset:7168
	global_load_lds_dwordx4 v[144:145], off
	v_lshl_add_u64 v[144:145], s[0:1], 0, v[138:139]
	s_add_i32 m0, s29, 0xe000
	s_nop 0
	global_load_lds_dwordx4 v[144:145], off
	s_waitcnt vmcnt(8)
	s_waitcnt lgkmcnt(0)
	s_barrier
	s_setprio 1
	s_waitcnt lgkmcnt(0)
	v_mfma_f32_16x16x32_bf16 v[124:127], v[152:155], v[184:187], v[124:127]
	v_mfma_f32_16x16x32_bf16 v[120:123], v[160:163], v[184:187], v[120:123]
	v_mfma_f32_16x16x32_bf16 v[116:119], v[152:155], v[192:195], v[116:119]
	v_mfma_f32_16x16x32_bf16 v[108:111], v[160:163], v[192:195], v[108:111]
	v_mfma_f32_16x16x32_bf16 v[100:103], v[152:155], v[200:203], v[100:103]
	v_mfma_f32_16x16x32_bf16 v[92:95], v[160:163], v[200:203], v[92:95]
	v_mfma_f32_16x16x32_bf16 v[84:87], v[152:155], v[208:211], v[84:87]
	v_mfma_f32_16x16x32_bf16 v[76:79], v[160:163], v[208:211], v[76:79]
	v_mfma_f32_16x16x32_bf16 v[124:127], v[156:159], v[188:191], v[124:127]
	v_mfma_f32_16x16x32_bf16 v[120:123], v[164:167], v[188:191], v[120:123]
	v_mfma_f32_16x16x32_bf16 v[116:119], v[156:159], v[196:199], v[116:119]
	v_mfma_f32_16x16x32_bf16 v[108:111], v[164:167], v[196:199], v[108:111]
	v_mfma_f32_16x16x32_bf16 v[100:103], v[156:159], v[204:207], v[100:103]
	v_mfma_f32_16x16x32_bf16 v[92:95], v[164:167], v[204:207], v[92:95]
	v_mfma_f32_16x16x32_bf16 v[84:87], v[156:159], v[212:215], v[84:87]
	v_mfma_f32_16x16x32_bf16 v[76:79], v[164:167], v[212:215], v[76:79]
	s_setprio 0
	s_setprio 1
	v_mfma_f32_16x16x32_bf16 v[112:115], v[168:171], v[184:187], v[112:115]
	v_mfma_f32_16x16x32_bf16 v[104:107], v[176:179], v[184:187], v[104:107]
	v_mfma_f32_16x16x32_bf16 v[96:99], v[168:171], v[192:195], v[96:99]
	v_mfma_f32_16x16x32_bf16 v[88:91], v[176:179], v[192:195], v[88:91]
	v_mfma_f32_16x16x32_bf16 v[80:83], v[168:171], v[200:203], v[80:83]
	v_mfma_f32_16x16x32_bf16 v[72:75], v[176:179], v[200:203], v[72:75]
	v_mfma_f32_16x16x32_bf16 v[68:71], v[168:171], v[208:211], v[68:71]
	v_mfma_f32_16x16x32_bf16 v[64:67], v[176:179], v[208:211], v[64:67]
	v_mfma_f32_16x16x32_bf16 v[112:115], v[172:175], v[188:191], v[112:115]
	v_mfma_f32_16x16x32_bf16 v[104:107], v[180:183], v[188:191], v[104:107]
	v_mfma_f32_16x16x32_bf16 v[96:99], v[172:175], v[196:199], v[96:99]
	v_mfma_f32_16x16x32_bf16 v[88:91], v[180:183], v[196:199], v[88:91]
	v_mfma_f32_16x16x32_bf16 v[80:83], v[172:175], v[204:207], v[80:83]
	v_mfma_f32_16x16x32_bf16 v[72:75], v[180:183], v[204:207], v[72:75]
	v_mfma_f32_16x16x32_bf16 v[68:71], v[172:175], v[212:215], v[68:71]
	v_mfma_f32_16x16x32_bf16 v[64:67], v[180:183], v[212:215], v[64:67]
	s_setprio 0
	s_barrier
	s_add_i32 s69, s57, s41
	v_lshl_add_u64 v[144:145], s[30:31], 0, v[132:133]
	s_mov_b32 m0, s69
	ds_read_b128 v[184:187], v151 offset:16384
	ds_read_b128 v[188:191], v151 offset:17408
	ds_read_b128 v[192:195], v151 offset:18432
	ds_read_b128 v[196:199], v151 offset:19456
	ds_read_b128 v[200:203], v151 offset:20480
	ds_read_b128 v[204:207], v151 offset:21504
	ds_read_b128 v[208:211], v151 offset:22528
	ds_read_b128 v[212:215], v151 offset:23552
	global_load_lds_dwordx4 v[144:145], off
	s_add_i32 m0, s69, 0x2000
	s_add_u32 s70, s30, 0x40000
	v_lshl_add_u64 v[216:217], s[30:31], 0, v[128:129]
	s_addc_u32 s71, s31, 0
	s_add_i32 s69, s58, s41
	global_load_lds_dwordx4 v[216:217], off
	v_lshl_add_u64 v[218:219], s[70:71], 0, v[132:133]
	s_mov_b32 m0, s69
	v_lshl_add_u64 v[220:221], s[34:35], 0, v[130:131]
	global_load_lds_dwordx4 v[218:219], off
	v_lshl_add_u64 v[218:219], s[70:71], 0, v[128:129]
	s_add_i32 m0, s69, 0x2000
	s_nop 0
	global_load_lds_dwordx4 v[218:219], off
	v_lshl_add_u64 v[218:219], s[34:35], 0, v[134:135]
	s_mov_b32 m0, s29
	s_nop 0
	global_load_lds_dwordx4 v[218:219], off
	s_mov_b32 m0, s43
	s_nop 0
	global_load_lds_dwordx4 v[220:221], off
	s_waitcnt vmcnt(8)
	s_waitcnt lgkmcnt(0)
	s_mov_b32 s97, 0
	s_cmp_lg_u32 s98, 0
	s_cbranch_scc0 .Lmy_df_vz_done
	s_cmp_eq_u32 s68, 12
	s_cbranch_scc1 .Lmy_df_vz_done
	s_mov_b32 s97, 1
	s_cmp_eq_u32 s68, 0
	s_cbranch_scc1 .Lmy_df_vz_b1
	s_cmp_eq_u32 s68, 2
	s_cbranch_scc1 .Lmy_df_vz_b2
	s_cmp_eq_u32 s68, 4
	s_cbranch_scc1 .Lmy_df_vz_b3
	s_cmp_eq_u32 s68, 6
	s_cbranch_scc1 .Lmy_df_vz_b4
	s_cmp_eq_u32 s68, 8
	s_cbranch_scc1 .Lmy_df_vz_b5
	s_cmp_eq_u32 s68, 10
	s_cbranch_scc1 .Lmy_df_vz_b6
	global_store_dwordx4 v[252:253], v[224:227], off offset:256
	s_nop 1
	v_add_co_u32_e32 v252, vcc, 0x8000, v252
	s_nop 1
	v_addc_co_u32_e32 v253, vcc, 0, v253, vcc
	s_branch .Lmy_df_vz_done
.Lmy_df_vz_b1:
	global_store_dwordx4 v[252:253], v[228:231], off
	s_branch .Lmy_df_vz_done
.Lmy_df_vz_b2:
	global_store_dwordx4 v[252:253], v[232:235], off offset:256
	s_nop 1
	v_add_co_u32_e32 v252, vcc, 0x8000, v252
	s_nop 1
	v_addc_co_u32_e32 v253, vcc, 0, v253, vcc
	s_branch .Lmy_df_vz_done
; __device__ __forceinline__ u32x4 pack8(const f32x4 a, const f32x4 b) { u32x4 w; w.x = cvt_pk_bf16(a[0], a[1]); w.y = cvt_pk_bf16(a[2], a[3]); w.z = cvt_pk_bf16(b[0], b[1]); w.w = cvt_pk_bf16(b[2], b[3]); return w; }
; #define PG8_STAGE(bufoff, gbase, voff) do { _Pragma("unroll") for (int _i = 0; _i < 2; ++_i) \
;         __builtin_amdgcn_global_load_lds((const unsigned*)((const char*)(gbase) + (voff)[_i]), (PG8_LAS unsigned*)(lds + (bufoff) + ldsw + _i * 8192), 16, 0, 0); } while (0)
; #define PG8_LDA(dst, b, h) do { _Pragma("unroll") for (int m = 0; m < 4; ++m) _Pragma("unroll") for (int k = 0; k < 2; ++k) dst[m][k] = *(const PG8_LAS bf16x8*)(lds + PG8_SA(b, h) + aoff + m * 2048 + k * 1024); } while (0)
; #define PG8_LDB(dst, b, h) do { _Pragma("unroll") for (int n = 0; n < 2; ++n) _Pragma("unroll") for (int k = 0; k < 2; ++k) dst[n][k] = *(const PG8_LAS bf16x8*)(lds + PG8_SB(b, h) + boff + n * 2048 + k * 1024); } while (0)
; #define PG8_WAIT_V(n) asm volatile("s_waitcnt vmcnt(" #n ")" ::: "memory")
; #define PG8_WAIT_L(n) asm volatile("s_waitcnt lgkmcnt(" #n ")" ::: "memory")
; #define PG8_BAR __builtin_amdgcn_s_barrier()
; #define PG8_SCHED __builtin_amdgcn_sched_barrier(0)
;     __device__ __forceinline__ void operator()(const f32x4 (&acc)[2][2][4][2], const Unit& u, int wr, int wc, int fr, int fq) const {
;     ...
;             for (int m = 0; m < 4; ++m) { bf16_t* rowp = O + (size_t)(row0 + ai * HALF + m * 16) * ldc + col0;
; #pragma unroll
;                 for (int bj = 0; bj < 2; ++bj) *(u32x4*)(rowp + bj * HALF) = pack8(acc[ai][bj][m][0], acc[ai][bj][m][1]); }
; template <class Epi, class Sched, bool ALIGN_EPI = false, bool SP2 = false>
; __device__ __forceinline__ void gemm_phase(PG8_LAS unsigned char* lds, const Gemm g, const Sched& S, const Epi& E, const int tid_in) {
;     ...
;             PG8_WAIT_V(8); PG8_WAIT_L(0); PG8_BAR; PG8_MMA(0, 0, At, B0); PG8_MMA(0, 1, At, B1); PG8_BAR; PG8_SCHED;
;             PG8_LDA(At, 0, 1); PG8_STAGE(PG8_SB(0, 0), b2, voffB); PG8_STAGE(PG8_SB(0, 1), b2 + hstep, voffB); PG8_STAGE(PG8_SA(0, 0), a2, voffA);
;             PG8_WAIT_V(8); PG8_WAIT_L(0); PG8_BAR; PG8_MMA(1, 0, At, B0); PG8_MMA(1, 1, At, B1); PG8_BAR; PG8_SCHED;
;             PG8_LDB(B0, 1, 0); PG8_LDB(B1, 1, 1); PG8_SCHED; PG8_LDA(At, 1, 0); PG8_STAGE(PG8_SA(0, 1), a2 + hstep, voffA);
.Lmy_df_vz_b3:
	global_store_dwordx4 v[252:253], v[236:239], off
	s_branch .Lmy_df_vz_done
.Lmy_df_vz_b4:
	global_store_dwordx4 v[252:253], v[240:243], off offset:256
	s_nop 1
	v_add_co_u32_e32 v252, vcc, 0x8000, v252
	s_nop 1
	v_addc_co_u32_e32 v253, vcc, 0, v253, vcc
	s_branch .Lmy_df_vz_done
.Lmy_df_vz_b5:
	global_store_dwordx4 v[252:253], v[244:247], off
	s_branch .Lmy_df_vz_done
.Lmy_df_vz_b6:
	global_store_dwordx4 v[252:253], v[248:251], off offset:256
.Lmy_df_vz_done:
	s_barrier
	s_setprio 1
	s_waitcnt lgkmcnt(0)
	v_mfma_f32_16x16x32_bf16 v[60:63], v[152:155], v[184:187], v[60:63]
	v_mfma_f32_16x16x32_bf16 v[56:59], v[160:163], v[184:187], v[56:59]
	v_mfma_f32_16x16x32_bf16 v[52:55], v[152:155], v[192:195], v[52:55]
	v_mfma_f32_16x16x32_bf16 v[44:47], v[160:163], v[192:195], v[44:47]
	v_mfma_f32_16x16x32_bf16 v[36:39], v[152:155], v[200:203], v[36:39]
	v_mfma_f32_16x16x32_bf16 v[28:31], v[160:163], v[200:203], v[28:31]
	v_mfma_f32_16x16x32_bf16 v[20:23], v[152:155], v[208:211], v[20:23]
	v_mfma_f32_16x16x32_bf16 v[12:15], v[160:163], v[208:211], v[12:15]
	v_mfma_f32_16x16x32_bf16 v[60:63], v[156:159], v[188:191], v[60:63]
	v_mfma_f32_16x16x32_bf16 v[56:59], v[164:167], v[188:191], v[56:59]
	v_mfma_f32_16x16x32_bf16 v[52:55], v[156:159], v[196:199], v[52:55]
	v_mfma_f32_16x16x32_bf16 v[44:47], v[164:167], v[196:199], v[44:47]
	v_mfma_f32_16x16x32_bf16 v[36:39], v[156:159], v[204:207], v[36:39]
	v_mfma_f32_16x16x32_bf16 v[28:31], v[164:167], v[204:207], v[28:31]
	v_mfma_f32_16x16x32_bf16 v[20:23], v[156:159], v[212:215], v[20:23]
	v_mfma_f32_16x16x32_bf16 v[12:15], v[164:167], v[212:215], v[12:15]
	s_setprio 0
	s_setprio 1
	v_mfma_f32_16x16x32_bf16 v[48:51], v[168:171], v[184:187], v[48:51]
	v_mfma_f32_16x16x32_bf16 v[40:43], v[176:179], v[184:187], v[40:43]
	v_mfma_f32_16x16x32_bf16 v[32:35], v[168:171], v[192:195], v[32:35]
	v_mfma_f32_16x16x32_bf16 v[24:27], v[176:179], v[192:195], v[24:27]
	v_mfma_f32_16x16x32_bf16 v[16:19], v[168:171], v[200:203], v[16:19]
	v_mfma_f32_16x16x32_bf16 v[8:11], v[176:179], v[200:203], v[8:11]
	v_mfma_f32_16x16x32_bf16 v[4:7], v[168:171], v[208:211], v[4:7]
	v_mfma_f32_16x16x32_bf16 v[0:3], v[176:179], v[208:211], v[0:3]
	v_mfma_f32_16x16x32_bf16 v[48:51], v[172:175], v[188:191], v[48:51]
	v_mfma_f32_16x16x32_bf16 v[40:43], v[180:183], v[188:191], v[40:43]
	v_mfma_f32_16x16x32_bf16 v[32:35], v[172:175], v[196:199], v[32:35]
	v_mfma_f32_16x16x32_bf16 v[24:27], v[180:183], v[196:199], v[24:27]
	v_mfma_f32_16x16x32_bf16 v[16:19], v[172:175], v[204:207], v[16:19]
	v_mfma_f32_16x16x32_bf16 v[8:11], v[180:183], v[204:207], v[8:11]
	v_mfma_f32_16x16x32_bf16 v[4:7], v[172:175], v[212:215], v[4:7]
	v_mfma_f32_16x16x32_bf16 v[0:3], v[180:183], v[212:215], v[0:3]
	s_setprio 0
	s_barrier
	s_add_i32 s69, 0, 0x18000
	s_add_i32 s70, 0, 0x1c000
	v_add_u32_e32 v164, s69, v147
	v_add_u32_e32 v180, s70, v147
	ds_read_b128 v[152:155], v164
	ds_read_b128 v[156:159], v164 offset:1024
	ds_read_b128 v[160:163], v164 offset:2048
	ds_read_b128 v[164:167], v164 offset:3072
	ds_read_b128 v[168:171], v180
	ds_read_b128 v[172:175], v180 offset:1024
	ds_read_b128 v[176:179], v180 offset:2048
	ds_read_b128 v[180:183], v180 offset:3072
	s_add_u32 s34, s34, 0x40000
	s_addc_u32 s35, s35, 0
	s_mov_b32 m0, s44
	v_lshl_add_u64 v[222:223], s[34:35], 0, v[134:135]
	ds_read_b128 v[184:187], v151 offset:32768
	ds_read_b128 v[188:191], v151 offset:33792
	ds_read_b128 v[192:195], v151 offset:34816
	ds_read_b128 v[196:199], v151 offset:35840
	ds_read_b128 v[200:203], v151 offset:36864
	ds_read_b128 v[204:207], v151 offset:37888
	ds_read_b128 v[208:211], v151 offset:38912
	ds_read_b128 v[212:215], v151 offset:39936
	global_load_lds_dwordx4 v[222:223], off
	v_lshl_add_u64 v[222:223], s[34:35], 0, v[130:131]
	s_mov_b32 m0, s45
	s_nop 0
	global_load_lds_dwordx4 v[222:223], off
	s_cmp_lg_u32 s97, 0
	s_cbranch_scc1 .Lmy_df_vz_w3b
	s_waitcnt vmcnt(8)
	s_branch .Lmy_df_vz_w3c
; #define PG8_STAGE(bufoff, gbase, voff) do { _Pragma("unroll") for (int _i = 0; _i < 2; ++_i) \
;         __builtin_amdgcn_global_load_lds((const unsigned*)((const char*)(gbase) + (voff)[_i]), (PG8_LAS unsigned*)(lds + (bufoff) + ldsw + _i * 8192), 16, 0, 0); } while (0)
; #define PG8_LDA(dst, b, h) do { _Pragma("unroll") for (int m = 0; m < 4; ++m) _Pragma("unroll") for (int k = 0; k < 2; ++k) dst[m][k] = *(const PG8_LAS bf16x8*)(lds + PG8_SA(b, h) + aoff + m * 2048 + k * 1024); } while (0)
; #define PG8_LDB(dst, b, h) do { _Pragma("unroll") for (int n = 0; n < 2; ++n) _Pragma("unroll") for (int k = 0; k < 2; ++k) dst[n][k] = *(const PG8_LAS bf16x8*)(lds + PG8_SB(b, h) + boff + n * 2048 + k * 1024); } while (0)
; #define PG8_MMA(ai, bj, At, Bt) do { __builtin_amdgcn_s_setprio(1); _Pragma("unroll") for (int m = 0; m < 4; ++m) _Pragma("unroll") for (int n = 0; n < 2; ++n) _Pragma("unroll") for (int k = 0; k < 2; ++k) \
;         acc[ai][bj][m][n] = __builtin_amdgcn_mfma_f32_16x16x32_bf16(Bt[n][k], At[m][k], acc[ai][bj][m][n], 0, 0, 0); __builtin_amdgcn_s_setprio(0); } while (0)
; #define PG8_WAIT_V(n) asm volatile("s_waitcnt vmcnt(" #n ")" ::: "memory")
; #define PG8_WAIT_L(n) asm volatile("s_waitcnt lgkmcnt(" #n ")" ::: "memory")
; #define PG8_BAR __builtin_amdgcn_s_barrier()
; #define PG8_SCHED __builtin_amdgcn_sched_barrier(0)
; template <class Epi, class Sched, bool ALIGN_EPI = false, bool SP2 = false>
; __device__ __forceinline__ void gemm_phase(PG8_LAS unsigned char* lds, const Gemm g, const Sched& S, const Epi& E, const int tid_in) {
;     ...
;             PG8_WAIT_V(8); PG8_WAIT_L(0); PG8_BAR; PG8_MMA(1, 0, At, B0); PG8_MMA(1, 1, At, B1); PG8_BAR; PG8_SCHED;
;             PG8_LDB(B0, 1, 0); PG8_LDB(B1, 1, 1); PG8_SCHED; PG8_LDA(At, 1, 0); PG8_STAGE(PG8_SA(0, 1), a2 + hstep, voffA);
;             PG8_WAIT_V(8); PG8_WAIT_L(0); PG8_BAR; PG8_MMA(0, 0, At, B0); PG8_MMA(0, 1, At, B1); PG8_BAR; PG8_SCHED;
;             PG8_LDA(At, 1, 1); PG8_STAGE(PG8_SB(1, 0), b3, voffB); PG8_STAGE(PG8_SB(1, 1), b3 + hstep, voffB); PG8_STAGE(PG8_SA(1, 0), a3, voffA);
.Lmy_df_vz_w3b:
	s_waitcnt vmcnt(9)
.Lmy_df_vz_w3c:
	s_waitcnt lgkmcnt(0)
	s_barrier
	s_setprio 1
	s_waitcnt lgkmcnt(0)
	v_mfma_f32_16x16x32_bf16 v[124:127], v[152:155], v[184:187], v[124:127]
	v_mfma_f32_16x16x32_bf16 v[120:123], v[160:163], v[184:187], v[120:123]
	v_mfma_f32_16x16x32_bf16 v[116:119], v[152:155], v[192:195], v[116:119]
	v_mfma_f32_16x16x32_bf16 v[108:111], v[160:163], v[192:195], v[108:111]
	v_mfma_f32_16x16x32_bf16 v[100:103], v[152:155], v[200:203], v[100:103]
	v_mfma_f32_16x16x32_bf16 v[92:95], v[160:163], v[200:203], v[92:95]
	v_mfma_f32_16x16x32_bf16 v[84:87], v[152:155], v[208:211], v[84:87]
	v_mfma_f32_16x16x32_bf16 v[76:79], v[160:163], v[208:211], v[76:79]
	v_mfma_f32_16x16x32_bf16 v[124:127], v[156:159], v[188:191], v[124:127]
	v_mfma_f32_16x16x32_bf16 v[120:123], v[164:167], v[188:191], v[120:123]
	v_mfma_f32_16x16x32_bf16 v[116:119], v[156:159], v[196:199], v[116:119]
	v_mfma_f32_16x16x32_bf16 v[108:111], v[164:167], v[196:199], v[108:111]
	v_mfma_f32_16x16x32_bf16 v[100:103], v[156:159], v[204:207], v[100:103]
	v_mfma_f32_16x16x32_bf16 v[92:95], v[164:167], v[204:207], v[92:95]
	v_mfma_f32_16x16x32_bf16 v[84:87], v[156:159], v[212:215], v[84:87]
	v_mfma_f32_16x16x32_bf16 v[76:79], v[164:167], v[212:215], v[76:79]
	s_setprio 0
	s_setprio 1
	v_mfma_f32_16x16x32_bf16 v[112:115], v[168:171], v[184:187], v[112:115]
	v_mfma_f32_16x16x32_bf16 v[104:107], v[176:179], v[184:187], v[104:107]
	v_mfma_f32_16x16x32_bf16 v[96:99], v[168:171], v[192:195], v[96:99]
	v_mfma_f32_16x16x32_bf16 v[88:91], v[176:179], v[192:195], v[88:91]
	v_mfma_f32_16x16x32_bf16 v[80:83], v[168:171], v[200:203], v[80:83]
	v_mfma_f32_16x16x32_bf16 v[72:75], v[176:179], v[200:203], v[72:75]
	v_mfma_f32_16x16x32_bf16 v[68:71], v[168:171], v[208:211], v[68:71]
	v_mfma_f32_16x16x32_bf16 v[64:67], v[176:179], v[208:211], v[64:67]
	v_mfma_f32_16x16x32_bf16 v[112:115], v[172:175], v[188:191], v[112:115]
	v_mfma_f32_16x16x32_bf16 v[104:107], v[180:183], v[188:191], v[104:107]
	v_mfma_f32_16x16x32_bf16 v[96:99], v[172:175], v[196:199], v[96:99]
	v_mfma_f32_16x16x32_bf16 v[88:91], v[180:183], v[196:199], v[88:91]
	v_mfma_f32_16x16x32_bf16 v[80:83], v[172:175], v[204:207], v[80:83]
	v_mfma_f32_16x16x32_bf16 v[72:75], v[180:183], v[204:207], v[72:75]
	v_mfma_f32_16x16x32_bf16 v[68:71], v[172:175], v[212:215], v[68:71]
	v_mfma_f32_16x16x32_bf16 v[64:67], v[180:183], v[212:215], v[64:67]
	s_setprio 0
	s_barrier
	s_add_i32 s34, s69, s41
	v_lshl_add_u64 v[144:145], v[144:145], 0, s[4:5]
	s_mov_b32 m0, s34
	ds_read_b128 v[184:187], v151 offset:49152
	ds_read_b128 v[188:191], v151 offset:50176
	ds_read_b128 v[192:195], v151 offset:51200
	ds_read_b128 v[196:199], v151 offset:52224
	ds_read_b128 v[200:203], v151 offset:53248
	ds_read_b128 v[204:207], v151 offset:54272
	ds_read_b128 v[208:211], v151 offset:55296
	ds_read_b128 v[212:215], v151 offset:56320
	global_load_lds_dwordx4 v[144:145], off
	s_add_i32 m0, s34, 0x2000
	s_add_u32 s30, s30, 0x40080
	v_lshl_add_u64 v[144:145], v[216:217], 0, s[4:5]
	s_addc_u32 s31, s31, 0
	s_add_i32 s34, s70, s41
	global_load_lds_dwordx4 v[144:145], off
	v_lshl_add_u64 v[144:145], s[30:31], 0, v[132:133]
	s_mov_b32 m0, s34
	s_nop 0
	global_load_lds_dwordx4 v[144:145], off
	v_lshl_add_u64 v[144:145], s[30:31], 0, v[128:129]
	s_add_i32 m0, s34, 0x2000
	s_nop 0
	global_load_lds_dwordx4 v[144:145], off
	v_lshl_add_u64 v[144:145], v[218:219], 0, s[4:5]
	s_mov_b32 m0, s52
	s_nop 0
	global_load_lds_dwordx4 v[144:145], off
	v_lshl_add_u64 v[144:145], v[220:221], 0, s[4:5]
	s_mov_b32 m0, s53
	s_nop 0
	global_load_lds_dwordx4 v[144:145], off
	s_cmp_lg_u32 s97, 0
	s_cbranch_scc1 .Lmy_df_vz_w4b
	s_waitcnt vmcnt(8)
	s_branch .Lmy_df_vz_w4c

; #define PG8_STAGE(bufoff, gbase, voff) do { _Pragma("unroll") for (int _i = 0; _i < 2; ++_i) \
;         __builtin_amdgcn_global_load_lds((const unsigned*)((const char*)(gbase) + (voff)[_i]), (PG8_LAS unsigned*)(lds + (bufoff) + ldsw + _i * 8192), 16, 0, 0); } while (0)
; #define PG8_LDA(dst, b, h) do { _Pragma("unroll") for (int m = 0; m < 4; ++m) _Pragma("unroll") for (int k = 0; k < 2; ++k) dst[m][k] = *(const PG8_LAS bf16x8*)(lds + PG8_SA(b, h) + aoff + m * 2048 + k * 1024); } while (0)
; #define PG8_MMA(ai, bj, At, Bt) do { __builtin_amdgcn_s_setprio(1); _Pragma("unroll") for (int m = 0; m < 4; ++m) _Pragma("unroll") for (int n = 0; n < 2; ++n) _Pragma("unroll") for (int k = 0; k < 2; ++k) \
;         acc[ai][bj][m][n] = __builtin_amdgcn_mfma_f32_16x16x32_bf16(Bt[n][k], At[m][k], acc[ai][bj][m][n], 0, 0, 0); __builtin_amdgcn_s_setprio(0); } while (0)
; #define PG8_WAIT_V(n) asm volatile("s_waitcnt vmcnt(" #n ")" ::: "memory")
; #define PG8_WAIT_L(n) asm volatile("s_waitcnt lgkmcnt(" #n ")" ::: "memory")
; #define PG8_BAR __builtin_amdgcn_s_barrier()
; #define PG8_SCHED __builtin_amdgcn_sched_barrier(0)
; template <class Epi, class Sched, bool ALIGN_EPI = false, bool SP2 = false>
; __device__ __forceinline__ void gemm_phase(PG8_LAS unsigned char* lds, const Gemm g, const Sched& S, const Epi& E, const int tid_in) {
;     ...
;             PG8_WAIT_V(8); PG8_WAIT_L(0); PG8_BAR; PG8_MMA(0, 0, At, B0); PG8_MMA(0, 1, At, B1); PG8_BAR; PG8_SCHED;
;             PG8_LDA(At, 1, 1); PG8_STAGE(PG8_SB(1, 0), b3, voffB); PG8_STAGE(PG8_SB(1, 1), b3 + hstep, voffB); PG8_STAGE(PG8_SA(1, 0), a3, voffA);
;             PG8_WAIT_V(8); PG8_WAIT_L(0); PG8_BAR; PG8_MMA(1, 0, At, B0); PG8_MMA(1, 1, At, B1); PG8_BAR; PG8_SCHED;
.Lmy_df_vz_w4c:
	s_waitcnt lgkmcnt(0)
	s_barrier
	s_setprio 1
	s_waitcnt lgkmcnt(0)
	v_mfma_f32_16x16x32_bf16 v[60:63], v[152:155], v[184:187], v[60:63]
	v_mfma_f32_16x16x32_bf16 v[56:59], v[160:163], v[184:187], v[56:59]
	v_mfma_f32_16x16x32_bf16 v[52:55], v[152:155], v[192:195], v[52:55]
	v_mfma_f32_16x16x32_bf16 v[44:47], v[160:163], v[192:195], v[44:47]
	v_mfma_f32_16x16x32_bf16 v[36:39], v[152:155], v[200:203], v[36:39]
	v_mfma_f32_16x16x32_bf16 v[28:31], v[160:163], v[200:203], v[28:31]
	v_mfma_f32_16x16x32_bf16 v[20:23], v[152:155], v[208:211], v[20:23]
	v_mfma_f32_16x16x32_bf16 v[12:15], v[160:163], v[208:211], v[12:15]
	v_mfma_f32_16x16x32_bf16 v[60:63], v[156:159], v[188:191], v[60:63]
	v_mfma_f32_16x16x32_bf16 v[56:59], v[164:167], v[188:191], v[56:59]
	v_mfma_f32_16x16x32_bf16 v[52:55], v[156:159], v[196:199], v[52:55]
	v_mfma_f32_16x16x32_bf16 v[44:47], v[164:167], v[196:199], v[44:47]
	v_mfma_f32_16x16x32_bf16 v[36:39], v[156:159], v[204:207], v[36:39]
	v_mfma_f32_16x16x32_bf16 v[28:31], v[164:167], v[204:207], v[28:31]
	v_mfma_f32_16x16x32_bf16 v[20:23], v[156:159], v[212:215], v[20:23]
	v_mfma_f32_16x16x32_bf16 v[12:15], v[164:167], v[212:215], v[12:15]
	s_setprio 0
	s_setprio 1
	v_mfma_f32_16x16x32_bf16 v[48:51], v[168:171], v[184:187], v[48:51]
	v_mfma_f32_16x16x32_bf16 v[40:43], v[176:179], v[184:187], v[40:43]
	v_mfma_f32_16x16x32_bf16 v[32:35], v[168:171], v[192:195], v[32:35]
	v_mfma_f32_16x16x32_bf16 v[24:27], v[176:179], v[192:195], v[24:27]
	v_mfma_f32_16x16x32_bf16 v[16:19], v[168:171], v[200:203], v[16:19]
	v_mfma_f32_16x16x32_bf16 v[8:11], v[176:179], v[200:203], v[8:11]
	v_mfma_f32_16x16x32_bf16 v[4:7], v[168:171], v[208:211], v[4:7]
	v_mfma_f32_16x16x32_bf16 v[0:3], v[176:179], v[208:211], v[0:3]
	v_mfma_f32_16x16x32_bf16 v[48:51], v[172:175], v[188:191], v[48:51]
	v_mfma_f32_16x16x32_bf16 v[40:43], v[180:183], v[188:191], v[40:43]
	v_mfma_f32_16x16x32_bf16 v[32:35], v[172:175], v[196:199], v[32:35]
	v_mfma_f32_16x16x32_bf16 v[24:27], v[180:183], v[196:199], v[24:27]
	v_mfma_f32_16x16x32_bf16 v[16:19], v[172:175], v[204:207], v[16:19]
	v_mfma_f32_16x16x32_bf16 v[8:11], v[180:183], v[204:207], v[8:11]
	v_mfma_f32_16x16x32_bf16 v[4:7], v[172:175], v[212:215], v[4:7]
	v_mfma_f32_16x16x32_bf16 v[0:3], v[180:183], v[212:215], v[0:3]
	s_setprio 0
	s_barrier
	s_add_i32 s68, s68, 2
	s_add_u32 s0, s0, 0x100
	s_addc_u32 s1, s1, 0
	s_add_u32 s66, s66, 0x100
	s_addc_u32 s67, s67, 0
	s_cmp_gt_u32 s68, 13
	s_cbranch_scc0 .LBB0_739
	s_and_b64 vcc, exec, s[6:7]
	s_cbranch_vccz .LBB0_742
	s_barrier
; __device__ __forceinline__ u32x4 pack8(const f32x4 a, const f32x4 b) { u32x4 w; w.x = cvt_pk_bf16(a[0], a[1]); w.y = cvt_pk_bf16(a[2], a[3]); w.z = cvt_pk_bf16(b[0], b[1]); w.w = cvt_pk_bf16(b[2], b[3]); return w; }
;     __device__ __forceinline__ void operator()(const f32x4 (&acc)[2][2][4][2], const Unit& u, int wr, int wc, int fr, int fq) const {
;         const bool first = u.pn < nsplit; bf16_t* O = first ? O1 : O2;
;         const int row0 = u.pm * BM + wr * 64 + fr, col0 = (first ? u.pn : u.pn - nsplit) * BM + wc * 32 + 8 * fq;
; #pragma unroll
;         for (int ai = 0; ai < 2; ++ai)
; #pragma unroll
;             for (int m = 0; m < 4; ++m) { bf16_t* rowp = O + (size_t)(row0 + ai * HALF + m * 16) * ldc + col0;
; #pragma unroll
;                 for (int bj = 0; bj < 2; ++bj) *(u32x4*)(rowp + bj * HALF) = pack8(acc[ai][bj][m][0], acc[ai][bj][m][1]); }
;     }
.LBB0_742:
	s_cmp_lt_i32 s63, 4
	s_cselect_b32 s0, s49, s51
	v_mov_b32_e32 v145, s0
	s_cselect_b32 s0, 0, -4
	s_cselect_b32 s1, s48, s50
	s_add_i32 s0, s0, s63
	v_lshl_add_u32 v152, s28, 8, v146
	v_lshl_or_b32 v154, s0, 8, v148
	v_mov_b32_e32 v144, s1
	v_ashrrev_i32_e32 v155, 31, v154
	v_ashrrev_i32_e32 v153, 31, v152
	v_lshl_add_u64 v[154:155], v[154:155], 1, v[144:145]
	v_lshlrev_b64 v[144:145], 11, v[152:153]
	v_lshl_add_u64 v[144:145], v[154:155], 0, v[144:145]
	v_cvt_pk_bf16_f32 v124, v124, v125
	v_cvt_pk_bf16_f32 v125, v126, v127
	v_cvt_pk_bf16_f32 v126, v120, v121
	v_cvt_pk_bf16_f32 v127, v122, v123
	global_store_dwordx4 v[144:145], v[124:127], off
	v_cvt_pk_bf16_f32 v112, v112, v113
	v_cvt_pk_bf16_f32 v113, v114, v115
	v_cvt_pk_bf16_f32 v114, v104, v105
	v_or_b32_e32 v104, 16, v152
	v_ashrrev_i32_e32 v105, 31, v104
	v_lshlrev_b64 v[104:105], 11, v[104:105]
	v_cvt_pk_bf16_f32 v115, v106, v107
	global_store_dwordx4 v[144:145], v[112:115], off offset:256
	s_mov_b64 s[0:1], -1
	s_nop 0
	v_lshl_add_u64 v[112:113], v[154:155], 0, v[104:105]
	v_cvt_pk_bf16_f32 v104, v116, v117
	v_cvt_pk_bf16_f32 v105, v118, v119
	v_cvt_pk_bf16_f32 v106, v108, v109
	v_cvt_pk_bf16_f32 v107, v110, v111
	global_store_dwordx4 v[112:113], v[104:107], off
	v_cvt_pk_bf16_f32 v96, v96, v97
	v_cvt_pk_bf16_f32 v97, v98, v99
	v_cvt_pk_bf16_f32 v98, v88, v89
	v_or_b32_e32 v88, 32, v152
	v_ashrrev_i32_e32 v89, 31, v88
	v_lshlrev_b64 v[88:89], 11, v[88:89]
	v_cvt_pk_bf16_f32 v99, v90, v91
	global_store_dwordx4 v[112:113], v[96:99], off offset:256
	s_nop 1
	v_lshl_add_u64 v[96:97], v[154:155], 0, v[88:89]
	v_cvt_pk_bf16_f32 v88, v100, v101
	v_cvt_pk_bf16_f32 v89, v102, v103
	v_cvt_pk_bf16_f32 v90, v92, v93
	v_cvt_pk_bf16_f32 v91, v94, v95
	global_store_dwordx4 v[96:97], v[88:91], off
	v_cvt_pk_bf16_f32 v80, v80, v81
	v_cvt_pk_bf16_f32 v81, v82, v83
	v_cvt_pk_bf16_f32 v82, v72, v73
	v_or_b32_e32 v72, 48, v152
	v_ashrrev_i32_e32 v73, 31, v72
	v_lshlrev_b64 v[72:73], 11, v[72:73]
	v_cvt_pk_bf16_f32 v83, v74, v75
	global_store_dwordx4 v[96:97], v[80:83], off offset:256
	s_nop 1
	v_lshl_add_u64 v[80:81], v[154:155], 0, v[72:73]
	v_cvt_pk_bf16_f32 v72, v84, v85
	v_cvt_pk_bf16_f32 v73, v86, v87
	v_cvt_pk_bf16_f32 v74, v76, v77
	v_cvt_pk_bf16_f32 v75, v78, v79
	global_store_dwordx4 v[80:81], v[72:75], off
	v_cvt_pk_bf16_f32 v68, v68, v69
	v_cvt_pk_bf16_f32 v69, v70, v71
	v_cvt_pk_bf16_f32 v70, v64, v65
	v_cvt_pk_bf16_f32 v71, v66, v67
	global_store_dwordx4 v[80:81], v[68:71], off offset:256
	v_cvt_pk_bf16_f32 v60, v60, v61
	v_cvt_pk_bf16_f32 v61, v62, v63
	v_cvt_pk_bf16_f32 v62, v56, v57
	v_add_co_u32_e32 v56, vcc, s59, v144
	v_lshl_add_u64 v[64:65], v[144:145], 0, s[10:11]
	s_nop 0
	v_addc_co_u32_e32 v57, vcc, 0, v145, vcc
	v_cvt_pk_bf16_f32 v63, v58, v59
	global_store_dwordx4 v[56:57], v[60:63], off
	v_cvt_pk_bf16_f32 v48, v48, v49
	v_cvt_pk_bf16_f32 v49, v50, v51
	v_cvt_pk_bf16_f32 v50, v40, v41
	v_cvt_pk_bf16_f32 v51, v42, v43
	v_mov_b64_e32 v[224:225], v[48:49]
	v_mov_b64_e32 v[226:227], v[50:51]
	v_mov_b64_e32 v[252:253], v[64:65]
	v_cvt_pk_bf16_f32 v40, v52, v53
	v_cvt_pk_bf16_f32 v41, v54, v55
	v_cvt_pk_bf16_f32 v42, v44, v45
	v_add_co_u32_e32 v44, vcc, s60, v144
	s_nop 0
	v_lshl_add_u64 v[48:49], v[144:145], 0, s[14:15]
	v_addc_co_u32_e32 v45, vcc, 0, v145, vcc
	v_cvt_pk_bf16_f32 v43, v46, v47
	v_mov_b64_e32 v[228:229], v[40:41]
	v_mov_b64_e32 v[230:231], v[42:43]
	v_cvt_pk_bf16_f32 v32, v32, v33
	v_cvt_pk_bf16_f32 v33, v34, v35
	v_cvt_pk_bf16_f32 v34, v24, v25
	v_cvt_pk_bf16_f32 v35, v26, v27
	v_mov_b64_e32 v[232:233], v[32:33]
	v_mov_b64_e32 v[234:235], v[34:35]
	v_cvt_pk_bf16_f32 v24, v36, v37
	v_cvt_pk_bf16_f32 v25, v38, v39
	v_cvt_pk_bf16_f32 v26, v28, v29
	v_add_co_u32_e32 v28, vcc, s61, v144
	s_nop 0
	v_lshl_add_u64 v[32:33], v[144:145], 0, s[16:17]
	v_addc_co_u32_e32 v29, vcc, 0, v145, vcc
	v_cvt_pk_bf16_f32 v27, v30, v31
	v_mov_b64_e32 v[236:237], v[24:25]
	v_mov_b64_e32 v[238:239], v[26:27]
	v_cvt_pk_bf16_f32 v16, v16, v17
	v_cvt_pk_bf16_f32 v17, v18, v19
	v_cvt_pk_bf16_f32 v18, v8, v9
	v_cvt_pk_bf16_f32 v19, v10, v11
	v_mov_b64_e32 v[240:241], v[16:17]
	v_mov_b64_e32 v[242:243], v[18:19]
	v_cvt_pk_bf16_f32 v8, v20, v21
	v_cvt_pk_bf16_f32 v9, v22, v23
	v_cvt_pk_bf16_f32 v10, v12, v13
	v_add_co_u32_e32 v12, vcc, s62, v144
	s_nop 0
	v_lshl_add_u64 v[16:17], v[144:145], 0, s[18:19]
	v_addc_co_u32_e32 v13, vcc, 0, v145, vcc
	s_andn2_b64 vcc, exec, s[2:3]
	v_cvt_pk_bf16_f32 v11, v14, v15
	v_mov_b64_e32 v[244:245], v[8:9]
	v_mov_b64_e32 v[246:247], v[10:11]
	v_cvt_pk_bf16_f32 v4, v4, v5
	v_cvt_pk_bf16_f32 v5, v6, v7
	v_cvt_pk_bf16_f32 v6, v0, v1
	v_cvt_pk_bf16_f32 v7, v2, v3
	v_mov_b64_e32 v[248:249], v[4:5]
	v_mov_b64_e32 v[250:251], v[6:7]
	s_mov_b32 s98, 1
	s_cbranch_vccnz .LBB0_731
	s_andn2_b64 vcc, exec, s[12:13]
	s_cbranch_vccnz .LBB0_730
	s_barrier
	s_branch .LBB0_730
.LBB0_745:
	s_cmp_lg_u32 s98, 0
	s_cbranch_scc0 .Lmy_df_vz_flushed
	global_store_dwordx4 v[252:253], v[224:227], off offset:256
	s_nop 1
	v_add_co_u32_e32 v252, vcc, 0x8000, v252
	s_nop 1
	v_addc_co_u32_e32 v253, vcc, 0, v253, vcc
	global_store_dwordx4 v[252:253], v[228:231], off
	global_store_dwordx4 v[252:253], v[232:235], off offset:256
	s_nop 1
	v_add_co_u32_e32 v252, vcc, 0x8000, v252
	s_nop 1
	v_addc_co_u32_e32 v253, vcc, 0, v253, vcc
	global_store_dwordx4 v[252:253], v[236:239], off
	global_store_dwordx4 v[252:253], v[240:243], off offset:256
	s_nop 1
	v_add_co_u32_e32 v252, vcc, 0x8000, v252
	s_nop 1
	v_addc_co_u32_e32 v253, vcc, 0, v253, vcc
	global_store_dwordx4 v[252:253], v[244:247], off
	global_store_dwordx4 v[252:253], v[248:251], off offset:256
	s_mov_b32 s98, 0
